# GDN coefficient pass on the matrix cores: one f32 Gram product [K;Q].K^T per wave gives intra-group Akk/Mqk and the cross-group blocks (replaces compiler VALU dots + cross-Gram snippet)
# speedup vs baseline: 1.3050x; 1.0155x over previous
.LBB0_539:
	s_or_b64 exec, exec, s[0:1]
	v_bfe_u32 v25, v112, 1, 4
	v_subrev_co_u32_e32 v27, vcc, 10, v25
	s_xor_b64 s[4:5], vcc, -1
	s_waitcnt lgkmcnt(0)
	s_barrier
	v_and_b32_e32 v150, 15, v180
	v_bfe_u32 v151, v180, 4, 2
	v_lshrrev_b32_e32 v152, 6, v180
	v_and_b32_e32 v157, 7, v150
	v_lshl_add_u32 v153, v152, 3, v157
	v_mul_u32_u24_e32 v153, 0x210, v153
	v_lshl_add_u32 v133, v151, 4, v153
	v_and_b32_e32 v154, 8, v150
	v_sub_u32_e32 v154, 8, v154
	v_mul_u32_u24_e32 v154, 0x1080, v154
	v_add_u32_e32 v132, v133, v154
	v_add_u32_e32 v133, 0x8400, v133
	ds_read_b128 v[30:33], v132 offset:0
	ds_read_b128 v[62:65], v133 offset:0
	ds_read_b128 v[34:37], v132 offset:64
	ds_read_b128 v[66:69], v133 offset:64
	ds_read_b128 v[38:41], v132 offset:128
	ds_read_b128 v[70:73], v133 offset:128
	ds_read_b128 v[42:45], v132 offset:192
	ds_read_b128 v[74:77], v133 offset:192
	ds_read_b128 v[46:49], v132 offset:256
	ds_read_b128 v[78:81], v133 offset:256
	ds_read_b128 v[50:53], v132 offset:320
	ds_read_b128 v[82:85], v133 offset:320
	ds_read_b128 v[54:57], v132 offset:384
	ds_read_b128 v[86:89], v133 offset:384
	ds_read_b128 v[58:61], v132 offset:448
	ds_read_b128 v[90:93], v133 offset:448
	v_lshrrev_b32_e32 v155, 1, v151
	v_and_b32_e32 v156, 1, v151
	v_lshl_add_u32 v153, v152, 1, v156
	v_lshlrev_b32_e32 v135, 4, v153
	v_add_u32_e32 v137, 0x21900, v135
	v_add_u32_e32 v135, 0x21800, v135
	v_lshl_add_u32 v136, v152, 3, v157
	v_lshlrev_b32_e32 v136, 2, v136
	v_add_u32_e32 v136, 0x21800, v136
	ds_read_b128 v[140:143], v135
	ds_read_b128 v[144:147], v137
	ds_read_b32 v148, v136
	v_lshl_add_u32 v134, v152, 1, v155
	v_lshlrev_b32_e32 v134, 8, v134
	v_lshl_add_u32 v134, v156, 7, v134
	v_lshl_add_u32 v134, v157, 2, v134
	v_add_u32_e32 v134, 0x14800, v134
	v_lshrrev_b32_e32 v153, 2, v157
	v_cmp_eq_u32_e32 vcc, v156, v153
	v_and_b32_e32 v158, 3, v157
	v_sub_u32_e32 v154, 1, v155
	v_add_u32_e32 v158, v158, v154
	v_mov_b32_e32 v154, 99
	v_cndmask_b32_e32 v158, v154, v158, vcc
	v_cmp_gt_u32_e32 vcc, v156, v153
	v_mov_b32_e32 v160, 1.0
	s_nop 1
	v_cndmask_b32_e32 v159, 0, v160, vcc
	v_cmp_eq_u32_e64 s[80:81], 1, v155
	v_cmp_ge_u32_e64 s[0:1], 1, v158
	v_cmp_ge_u32_e64 s[4:5], 2, v158
	v_cmp_ge_u32_e64 s[6:7], 3, v158
	v_cmp_ge_u32_e32 vcc, 0, v158
	s_waitcnt lgkmcnt(0)
	v_mfma_f32_16x16x4_f32 v[96:99], v30, v62, 0
	v_mfma_f32_16x16x4_f32 v[100:103], v31, v63, 0
	v_mfma_f32_16x16x4_f32 v[96:99], v32, v64, v[96:99]
	v_mfma_f32_16x16x4_f32 v[100:103], v33, v65, v[100:103]
	v_sub_f32_e32 v164, v140, v148
	v_sub_f32_e32 v165, v141, v148
	v_sub_f32_e32 v166, v142, v148
	v_sub_f32_e32 v167, v143, v148
	v_min_f32_e32 v164, 0, v164
	v_min_f32_e32 v165, 0, v165
	v_min_f32_e32 v166, 0, v166
	v_min_f32_e32 v167, 0, v167
	v_mul_f32_e32 v164, 0x3fb8aa3b, v164
	v_mul_f32_e32 v165, 0x3fb8aa3b, v165
	v_mul_f32_e32 v166, 0x3fb8aa3b, v166
	v_mul_f32_e32 v167, 0x3fb8aa3b, v167
	v_exp_f32_e32 v164, v164
	v_exp_f32_e32 v165, v165
	v_exp_f32_e32 v166, v166
	v_exp_f32_e32 v167, v167
	v_mfma_f32_16x16x4_f32 v[96:99], v34, v66, v[96:99]
	v_mfma_f32_16x16x4_f32 v[100:103], v35, v67, v[100:103]
	v_mfma_f32_16x16x4_f32 v[96:99], v36, v68, v[96:99]
	v_mfma_f32_16x16x4_f32 v[100:103], v37, v69, v[100:103]
	v_cndmask_b32_e64 v144, v144, v160, s[80:81]
	v_cndmask_b32_e64 v145, v145, v160, s[80:81]
	v_cndmask_b32_e64 v146, v146, v160, s[80:81]
	v_cndmask_b32_e64 v147, v147, v160, s[80:81]
	v_mul_f32_e32 v164, v164, v144
	v_mul_f32_e32 v165, v165, v145
	v_mul_f32_e32 v166, v166, v146
	v_mul_f32_e32 v167, v167, v147
	v_cndmask_b32_e32 v164, v159, v164, vcc
	v_cndmask_b32_e64 v165, v159, v165, s[0:1]
	v_cndmask_b32_e64 v166, v159, v166, s[4:5]
	v_cndmask_b32_e64 v167, v159, v167, s[6:7]
	v_mfma_f32_16x16x4_f32 v[96:99], v38, v70, v[96:99]
	v_mfma_f32_16x16x4_f32 v[100:103], v39, v71, v[100:103]
	v_mfma_f32_16x16x4_f32 v[96:99], v40, v72, v[96:99]
	v_mfma_f32_16x16x4_f32 v[100:103], v41, v73, v[100:103]
	v_mfma_f32_16x16x4_f32 v[96:99], v42, v74, v[96:99]
	v_mfma_f32_16x16x4_f32 v[100:103], v43, v75, v[100:103]
	v_mfma_f32_16x16x4_f32 v[96:99], v44, v76, v[96:99]
	v_mfma_f32_16x16x4_f32 v[100:103], v45, v77, v[100:103]
	v_mfma_f32_16x16x4_f32 v[96:99], v46, v78, v[96:99]
	v_mfma_f32_16x16x4_f32 v[100:103], v47, v79, v[100:103]
	v_mfma_f32_16x16x4_f32 v[96:99], v48, v80, v[96:99]
	v_mfma_f32_16x16x4_f32 v[100:103], v49, v81, v[100:103]
	v_mfma_f32_16x16x4_f32 v[96:99], v50, v82, v[96:99]
	v_mfma_f32_16x16x4_f32 v[100:103], v51, v83, v[100:103]
	v_mfma_f32_16x16x4_f32 v[96:99], v52, v84, v[96:99]
	v_mfma_f32_16x16x4_f32 v[100:103], v53, v85, v[100:103]
	v_mfma_f32_16x16x4_f32 v[96:99], v54, v86, v[96:99]
	v_mfma_f32_16x16x4_f32 v[100:103], v55, v87, v[100:103]
	v_mfma_f32_16x16x4_f32 v[96:99], v56, v88, v[96:99]
	v_mfma_f32_16x16x4_f32 v[100:103], v57, v89, v[100:103]
	v_mfma_f32_16x16x4_f32 v[96:99], v58, v90, v[96:99]
	v_mfma_f32_16x16x4_f32 v[100:103], v59, v91, v[100:103]
	v_mfma_f32_16x16x4_f32 v[96:99], v60, v92, v[96:99]
	v_mfma_f32_16x16x4_f32 v[100:103], v61, v93, v[100:103]
	s_nop 7
	s_nop 2
	v_pk_add_f32 v[96:97], v[96:97], v[100:101]
	v_pk_add_f32 v[98:99], v[98:99], v[102:103]
	v_mul_f32_e32 v96, v96, v164
	v_mul_f32_e32 v97, v97, v165
	v_mul_f32_e32 v98, v98, v166
	v_mul_f32_e32 v99, v99, v167
	ds_write_b32 v134, v96 offset:0
	ds_write_b32 v134, v97 offset:32
	ds_write_b32 v134, v98 offset:64
	ds_write_b32 v134, v99 offset:96
	s_lshl_b32 s0, s17, 6
	s_add_i32 s72, s0, s16
	v_and_b32_e32 v128, 63, v112
	s_cmp_eq_u32 s17, 31
	s_waitcnt lgkmcnt(0)
	s_barrier
	s_cbranch_scc1 .LBB0_549
	s_add_i32 s0, s72, 64
	s_mov_b32 s1, s73
	v_ashrrev_i32_e32 v27, 31, v26
	v_lshlrev_b32_e32 v2, 1, v23
	v_mov_b32_e32 v3, v94
	v_ashrrev_i32_e32 v23, 31, v22
	v_ashrrev_i32_e32 v25, 31, v24
	v_lshl_add_u64 v[18:19], s[0:1], 0, v[26:27]
	v_mov_b64_e32 v[20:21], s[12:13]
	v_lshl_add_u64 v[10:11], s[8:9], 0, v[2:3]
	v_lshl_add_u64 v[2:3], s[0:1], 0, v[22:23]
	v_lshl_add_u64 v[12:13], s[0:1], 0, v[24:25]
	v_mad_u64_u32 v[20:21], s[4:5], v18, s83, v[20:21]
	v_mad_u64_u32 v[6:7], s[4:5], v2, s83, v[10:11]
	v_mad_u64_u32 v[14:15], s[4:5], v12, s83, v[10:11]
	v_mad_i32_i24 v21, v19, s83, v21
	v_lshlrev_b32_e32 v18, 1, v28
	v_mov_b32_e32 v19, v94
	v_mad_i32_i24 v7, v3, s83, v7
	v_mad_i32_i24 v15, v13, s83, v15
	v_lshl_add_u64 v[18:19], v[20:21], 0, v[18:19]
	v_or_b32_e32 v22, s0, v128
	v_mov_b64_e32 v[20:21], s[14:15]
	global_load_dwordx4 v[2:5], v[6:7], off
	s_nop 0
	global_load_dwordx4 v[6:9], v[6:7], off offset:1024
	s_nop 0
	global_load_dwordx4 v[10:13], v[14:15], off
	s_nop 0
	global_load_dwordx4 v[14:17], v[14:15], off offset:1024
	v_mad_u64_u32 v[22:23], s[0:1], v22, s87, v[20:21]
	global_load_dwordx4 v[18:21], v[18:19], off offset:2048
	s_nop 0
	global_load_dword v126, v[22:23], off offset:512
	global_load_dword v127, v[22:23], off offset:528
.LBB0_549:
	v_readfirstlane_b32 s0, v180
	s_nop 1
	s_cmpk_ge_u32 s0, 0x100
	s_cbranch_scc1 .Lgdn_done
	v_and_b32_e32 v166, 15, v180
	v_bfe_u32 v167, v180, 4, 2
	v_lshrrev_b32_e32 v168, 6, v180
	v_and_b32_e32 v177, 3, v166
	v_bfe_u32 v178, v166, 3, 1
	v_lshl_add_u32 v177, v178, 2, v177
	v_mul_u32_u24_e32 v177, 0x210, v177
	v_bfe_u32 v87, v166, 2, 1
	v_lshlrev_b32_e32 v87, 8, v87
	v_and_b32_e32 v178, 3, v166
	v_lshl_add_u32 v87, v178, 5, v87
	v_lshl_add_u32 v87, v167, 2, v87
	v_add_u32_e32 v87, 0x14880, v87
	v_and_b32_e32 v178, 4, v166
	v_sub_u32_e32 v178, 4, v178
	v_mul_u32_u24_e32 v178, 0x2100, v178
	v_lshl_add_u32 v169, v167, 4, v177
	v_add_u32_e32 v169, v169, v178
	v_mul_u32_u24_e32 v177, 0x210, v167
	v_lshl_add_u32 v170, v166, 2, v177
	v_add_u32_e32 v170, 0x8400, v170
	v_add_u32_e32 v237, 0x840, v170
	v_add_u32_e32 v95, 0x1080, v170
	v_lshlrev_b32_e32 v177, 6, v168
	v_lshl_add_u32 v177, v166, 2, v177
	v_add_u32_e32 v171, 0x10800, v177
	v_lshl_add_u32 v172, v167, 8, v177
	v_add_u32_e32 v172, 0x1d800, v172
	v_mov_b32_e32 v173, 0x14800
	v_lshlrev_b32_e32 v174, 5, v167
	v_add_u32_e32 v174, 0x14900, v174
	v_mov_b32_e32 v175, 0x21900
	v_lshl_add_u32 v176, v167, 2, v175
	v_cmp_eq_u32_e32 vcc, 1, v167
	v_cmp_eq_u32_e64 s[4:5], 2, v167
	v_cmp_eq_u32_e64 s[6:7], 3, v167
	ds_read_b128 v[22:25], v169 offset:0
	ds_read_b128 v[26:29], v169 offset:64
	ds_read_b128 v[30:33], v169 offset:128
	ds_read_b128 v[34:37], v169 offset:192
	ds_read_b128 v[38:41], v169 offset:256
	ds_read_b128 v[42:45], v169 offset:320
	ds_read_b128 v[46:49], v169 offset:384
	ds_read_b128 v[50:53], v169 offset:448
	ds_read2_b32 v[54:55], v170 offset0:0 offset1:16
	ds_read2_b32 v[56:57], v170 offset0:32 offset1:48
	ds_read2_b32 v[58:59], v170 offset0:64 offset1:80
	ds_read2_b32 v[60:61], v170 offset0:96 offset1:112
	ds_read2st64_b32 v[70:71], v171 offset0:0 offset1:1
	ds_read2st64_b32 v[72:73], v171 offset0:2 offset1:3
	ds_read_b128 v[132:135], v175 offset:0
	ds_read_b128 v[136:139], v175 offset:256
	ds_read_b32 v151, v176 offset:256
	ds_read_b32 v152, v176 offset:512
	ds_read_b32 v150, v173 offset:32
	ds_read_b64 v[148:149], v173 offset:64
	ds_read_b128 v[140:143], v173 offset:96
	ds_read_b128 v[144:147], v174 offset:0
	s_mov_b32 s1, 0
	s_waitcnt lgkmcnt(0)
	s_waitcnt lgkmcnt(1)
	v_mfma_f32_16x16x4_f32 v[96:99], v22, v184, 0
	v_mfma_f32_16x16x4_f32 v[100:103], v23, v185, 0
	v_mfma_f32_16x16x4_f32 v[96:99], v24, v186, v[96:99]
	v_mfma_f32_16x16x4_f32 v[100:103], v25, v187, v[100:103]
	v_mul_f32_e32 v129, v132, v70
	v_mul_f32_e32 v130, v133, v71
	v_mul_f32_e32 v131, v134, v72
	v_mul_f32_e32 v153, v135, v73
	v_mfma_f32_16x16x4_f32 v[96:99], v26, v188, v[96:99]
	v_mfma_f32_16x16x4_f32 v[100:103], v27, v189, v[100:103]
	v_mfma_f32_16x16x4_f32 v[96:99], v28, v190, v[96:99]
	v_mfma_f32_16x16x4_f32 v[100:103], v29, v191, v[100:103]
	v_mul_f32_e64 v114, -v132, v136
	v_mul_f32_e64 v115, -v133, v137
	v_mul_f32_e64 v116, -v134, v138
	v_mul_f32_e64 v117, -v135, v139
	v_mfma_f32_16x16x4_f32 v[96:99], v30, v192, v[96:99]
	v_mfma_f32_16x16x4_f32 v[100:103], v31, v193, v[100:103]
	v_mfma_f32_16x16x4_f32 v[96:99], v32, v194, v[96:99]
	v_mfma_f32_16x16x4_f32 v[100:103], v33, v195, v[100:103]
	v_mul_f32_e32 v240, v238, v139
	v_rcp_f32_e32 v89, v240
	v_readfirstlane_b32 s0, v240
	ds_read_b32 v86, v87 offset:0
	v_mfma_f32_16x16x4_f32 v[96:99], v34, v196, v[96:99]
	v_mfma_f32_16x16x4_f32 v[100:103], v35, v197, v[100:103]
	v_mfma_f32_16x16x4_f32 v[96:99], v36, v198, v[96:99]
	v_mfma_f32_16x16x4_f32 v[100:103], v37, v199, v[100:103]
	ds_read2_b32 v[62:63], v237 offset0:0 offset1:16
	ds_read2_b32 v[64:65], v237 offset0:32 offset1:48
	ds_read2_b32 v[66:67], v237 offset0:64 offset1:80
	ds_read2_b32 v[68:69], v237 offset0:96 offset1:112
	v_mfma_f32_16x16x4_f32 v[96:99], v38, v200, v[96:99]
	v_mfma_f32_16x16x4_f32 v[100:103], v39, v201, v[100:103]
	v_mfma_f32_16x16x4_f32 v[96:99], v40, v202, v[96:99]
	v_mfma_f32_16x16x4_f32 v[100:103], v41, v203, v[100:103]
	ds_read2st64_b32 v[74:75], v171 offset0:4 offset1:5
	ds_read2st64_b32 v[76:77], v171 offset0:6 offset1:7
	ds_read_b128 v[216:219], v175 offset:16
	ds_read_b128 v[220:223], v175 offset:272
	v_mfma_f32_16x16x4_f32 v[96:99], v42, v204, v[96:99]
	v_mfma_f32_16x16x4_f32 v[100:103], v43, v205, v[100:103]
	v_mfma_f32_16x16x4_f32 v[96:99], v44, v206, v[96:99]
	v_mfma_f32_16x16x4_f32 v[100:103], v45, v207, v[100:103]
	ds_read_b32 v235, v176 offset:272
	ds_read_b32 v236, v176 offset:528
	ds_read_b32 v234, v173 offset:176
	ds_read_b64 v[232:233], v173 offset:208
	v_mfma_f32_16x16x4_f32 v[96:99], v46, v208, v[96:99]
	v_mfma_f32_16x16x4_f32 v[100:103], v47, v209, v[100:103]
	v_mfma_f32_16x16x4_f32 v[96:99], v48, v210, v[96:99]
	v_mfma_f32_16x16x4_f32 v[100:103], v49, v211, v[100:103]
	ds_read_b128 v[224:227], v173 offset:240
	ds_read_b128 v[228:231], v174 offset:144
	v_mfma_f32_16x16x4_f32 v[96:99], v50, v212, v[96:99]
	v_mfma_f32_16x16x4_f32 v[100:103], v51, v213, v[100:103]
	v_mfma_f32_16x16x4_f32 v[96:99], v52, v214, v[96:99]
	v_mfma_f32_16x16x4_f32 v[100:103], v53, v215, v[100:103]
	s_nop 7
	s_nop 1
	v_pk_mul_f32 v[100:101], v[100:101], v[238:239] op_sel_hi:[1,0]
	v_pk_mul_f32 v[102:103], v[102:103], v[238:239] op_sel_hi:[1,0]
	v_pk_fma_f32 v[78:79], v[96:97], v[238:239], v[100:101] op_sel_hi:[1,0,1]
	v_pk_fma_f32 v[80:81], v[98:99], v[238:239], v[102:103] op_sel_hi:[1,0,1]
	v_pk_fma_f32 v[96:97], v[96:97], v[238:239], v[100:101] op_sel_hi:[1,0,1]
	v_pk_fma_f32 v[98:99], v[98:99], v[238:239], v[102:103] op_sel_hi:[1,0,1]
	s_nop 0
	v_permlane32_swap_b32_e32 v96, v78
	v_permlane32_swap_b32_e32 v97, v79
	v_permlane32_swap_b32_e32 v98, v80
	v_permlane32_swap_b32_e32 v99, v81
	v_mov_b32_e32 v82, v96
	v_mov_b32_e32 v83, v97
	v_mov_b32_e32 v84, v98
	v_mov_b32_e32 v85, v99
	s_nop 0
	v_permlane16_swap_b32_e32 v96, v82
	v_permlane16_swap_b32_e32 v97, v83
	v_permlane16_swap_b32_e32 v98, v84
	v_permlane16_swap_b32_e32 v99, v85
	v_fma_f32 v108, v114, v96, v129
	v_fma_f32 v109, v115, v97, v130
	v_fma_f32 v110, v116, v98, v131
	v_fma_f32 v111, v117, v99, v153
	v_fma_f32 v109, -v150, v108, v109
	v_fma_f32 v110, -v148, v108, v110
	v_fma_f32 v111, -v140, v108, v111
	v_fma_f32 v110, -v149, v109, v110
	v_fma_f32 v111, -v141, v109, v111
	v_fma_f32 v111, -v142, v110, v111
	v_cndmask_b32_e32 v182, v108, v109, vcc
	v_cndmask_b32_e64 v182, v182, v110, s[4:5]
	v_cndmask_b32_e64 v182, v182, v111, s[6:7]
	v_mul_f32_e32 v182, v152, v182
	s_cmp_lt_u32 s0, 0x2b800000
	s_cbranch_scc0 .Lgdn_nomat_0_0
	v_pk_mul_f32 v[184:185], v[184:185], v[240:241] op_sel_hi:[1,0]
	v_pk_mul_f32 v[186:187], v[186:187], v[240:241] op_sel_hi:[1,0]
	v_pk_mul_f32 v[188:189], v[188:189], v[240:241] op_sel_hi:[1,0]
	v_pk_mul_f32 v[190:191], v[190:191], v[240:241] op_sel_hi:[1,0]
	v_pk_mul_f32 v[192:193], v[192:193], v[240:241] op_sel_hi:[1,0]
	v_pk_mul_f32 v[194:195], v[194:195], v[240:241] op_sel_hi:[1,0]
	v_pk_mul_f32 v[196:197], v[196:197], v[240:241] op_sel_hi:[1,0]
	v_pk_mul_f32 v[198:199], v[198:199], v[240:241] op_sel_hi:[1,0]
	v_pk_mul_f32 v[200:201], v[200:201], v[240:241] op_sel_hi:[1,0]
	v_pk_mul_f32 v[202:203], v[202:203], v[240:241] op_sel_hi:[1,0]
	v_pk_mul_f32 v[204:205], v[204:205], v[240:241] op_sel_hi:[1,0]
	v_pk_mul_f32 v[206:207], v[206:207], v[240:241] op_sel_hi:[1,0]
	v_pk_mul_f32 v[208:209], v[208:209], v[240:241] op_sel_hi:[1,0]
	v_pk_mul_f32 v[210:211], v[210:211], v[240:241] op_sel_hi:[1,0]
	v_pk_mul_f32 v[212:213], v[212:213], v[240:241] op_sel_hi:[1,0]
	v_pk_mul_f32 v[214:215], v[214:215], v[240:241] op_sel_hi:[1,0]
	v_mov_b32_e32 v240, 1.0
	v_mov_b32_e32 v89, 1.0

.Lgdn_nomat_0_1:
	v_mov_b32_e32 v238, v240
	v_mul_f32_e32 v90, v182, v89
	s_nop 1
	v_mfma_f32_16x16x4_f32 v[184:187], v62, v90, v[184:187]
	v_mfma_f32_16x16x4_f32 v[188:191], v63, v90, v[188:191]
	v_mfma_f32_16x16x4_f32 v[192:195], v64, v90, v[192:195]
	v_mfma_f32_16x16x4_f32 v[196:199], v65, v90, v[196:199]
	v_mfma_f32_16x16x4_f32 v[200:203], v66, v90, v[200:203]
	v_mfma_f32_16x16x4_f32 v[204:207], v67, v90, v[204:207]
	v_mfma_f32_16x16x4_f32 v[208:211], v68, v90, v[208:211]
	v_mfma_f32_16x16x4_f32 v[212:215], v69, v90, v[212:215]
	v_cndmask_b32_e32 v183, v82, v83, vcc
	v_cndmask_b32_e64 v183, v183, v84, s[4:5]
	v_cndmask_b32_e64 v183, v183, v85, s[6:7]
	v_mul_f32_e32 v179, v235, v183
	v_fmac_f32_e32 v179, v228, v108
	v_fmac_f32_e32 v179, v229, v109
	v_fmac_f32_e32 v179, v230, v110
	v_fmac_f32_e32 v179, v231, v111
	ds_write_b32 v172, v179 offset:1024
	v_add_u32_e32 v170, 0x1080, v170
	v_add_u32_e32 v237, 0x1080, v237
	v_add_u32_e32 v95, 0x1080, v95
	s_waitcnt lgkmcnt(1)
	v_mfma_f32_16x16x4_f32 v[96:99], v22, v184, 0
	v_mfma_f32_16x16x4_f32 v[100:103], v23, v185, 0
	v_mfma_f32_16x16x4_f32 v[96:99], v24, v186, v[96:99]
	v_mfma_f32_16x16x4_f32 v[100:103], v25, v187, v[100:103]
	v_mul_f32_e32 v129, v132, v70
	v_mul_f32_e32 v130, v133, v71
	v_mul_f32_e32 v131, v134, v72
	v_mul_f32_e32 v153, v135, v73
	v_mfma_f32_16x16x4_f32 v[96:99], v26, v188, v[96:99]
	v_mfma_f32_16x16x4_f32 v[100:103], v27, v189, v[100:103]
	v_mfma_f32_16x16x4_f32 v[96:99], v28, v190, v[96:99]
	v_mfma_f32_16x16x4_f32 v[100:103], v29, v191, v[100:103]
	v_mul_f32_e64 v114, -v132, v136
	v_mul_f32_e64 v115, -v133, v137
	v_mul_f32_e64 v116, -v134, v138
	v_mul_f32_e64 v117, -v135, v139
	v_mfma_f32_16x16x4_f32 v[96:99], v30, v192, v[96:99]
	v_mfma_f32_16x16x4_f32 v[100:103], v31, v193, v[100:103]
	v_mfma_f32_16x16x4_f32 v[96:99], v32, v194, v[96:99]
	v_mfma_f32_16x16x4_f32 v[100:103], v33, v195, v[100:103]
	v_mul_f32_e32 v240, v238, v139
	v_rcp_f32_e32 v89, v240
	v_readfirstlane_b32 s0, v240
	ds_read_b32 v86, v87 offset:512
	v_mfma_f32_16x16x4_f32 v[96:99], v34, v196, v[96:99]
	v_mfma_f32_16x16x4_f32 v[100:103], v35, v197, v[100:103]
	v_mfma_f32_16x16x4_f32 v[96:99], v36, v198, v[96:99]
	v_mfma_f32_16x16x4_f32 v[100:103], v37, v199, v[100:103]
	ds_read2_b32 v[62:63], v237 offset0:0 offset1:16
	ds_read2_b32 v[64:65], v237 offset0:32 offset1:48
	ds_read2_b32 v[66:67], v237 offset0:64 offset1:80
	ds_read2_b32 v[68:69], v237 offset0:96 offset1:112
	v_mfma_f32_16x16x4_f32 v[96:99], v38, v200, v[96:99]
	v_mfma_f32_16x16x4_f32 v[100:103], v39, v201, v[100:103]
	v_mfma_f32_16x16x4_f32 v[96:99], v40, v202, v[96:99]
	v_mfma_f32_16x16x4_f32 v[100:103], v41, v203, v[100:103]
	ds_read2st64_b32 v[74:75], v171 offset0:12 offset1:13
	ds_read2st64_b32 v[76:77], v171 offset0:14 offset1:15
	ds_read_b128 v[216:219], v175 offset:48
	ds_read_b128 v[220:223], v175 offset:304
	v_mfma_f32_16x16x4_f32 v[96:99], v42, v204, v[96:99]
	v_mfma_f32_16x16x4_f32 v[100:103], v43, v205, v[100:103]
	v_mfma_f32_16x16x4_f32 v[96:99], v44, v206, v[96:99]
	v_mfma_f32_16x16x4_f32 v[100:103], v45, v207, v[100:103]
	ds_read_b32 v235, v176 offset:304
	ds_read_b32 v236, v176 offset:560
	ds_read_b32 v234, v173 offset:688
	ds_read_b64 v[232:233], v173 offset:720
	v_mfma_f32_16x16x4_f32 v[96:99], v46, v208, v[96:99]
	v_mfma_f32_16x16x4_f32 v[100:103], v47, v209, v[100:103]
	v_mfma_f32_16x16x4_f32 v[96:99], v48, v210, v[96:99]
	v_mfma_f32_16x16x4_f32 v[100:103], v49, v211, v[100:103]
	ds_read_b128 v[224:227], v173 offset:752
	ds_read_b128 v[228:231], v174 offset:656
	v_mfma_f32_16x16x4_f32 v[96:99], v50, v212, v[96:99]
	v_mfma_f32_16x16x4_f32 v[100:103], v51, v213, v[100:103]
	v_mfma_f32_16x16x4_f32 v[96:99], v52, v214, v[96:99]
	v_mfma_f32_16x16x4_f32 v[100:103], v53, v215, v[100:103]
	s_nop 7
	s_nop 1
	v_pk_mul_f32 v[100:101], v[100:101], v[238:239] op_sel_hi:[1,0]
	v_pk_mul_f32 v[102:103], v[102:103], v[238:239] op_sel_hi:[1,0]
	v_pk_fma_f32 v[78:79], v[96:97], v[238:239], v[100:101] op_sel_hi:[1,0,1]
	v_pk_fma_f32 v[80:81], v[98:99], v[238:239], v[102:103] op_sel_hi:[1,0,1]
	v_pk_fma_f32 v[96:97], v[96:97], v[238:239], v[100:101] op_sel_hi:[1,0,1]
	v_pk_fma_f32 v[98:99], v[98:99], v[238:239], v[102:103] op_sel_hi:[1,0,1]
	s_nop 0
	v_permlane32_swap_b32_e32 v96, v78
	v_permlane32_swap_b32_e32 v97, v79
	v_permlane32_swap_b32_e32 v98, v80
	v_permlane32_swap_b32_e32 v99, v81
	v_mov_b32_e32 v82, v96
	v_mov_b32_e32 v83, v97
	v_mov_b32_e32 v84, v98
	v_mov_b32_e32 v85, v99
	s_nop 0
	v_permlane16_swap_b32_e32 v96, v82
	v_permlane16_swap_b32_e32 v97, v83
	v_permlane16_swap_b32_e32 v98, v84
	v_permlane16_swap_b32_e32 v99, v85
	v_fma_f32 v108, v114, v96, v129
	v_fma_f32 v109, v115, v97, v130
	v_fma_f32 v110, v116, v98, v131
	v_fma_f32 v111, v117, v99, v153
	v_fma_f32 v109, -v150, v108, v109
	v_fma_f32 v110, -v148, v108, v110
	v_fma_f32 v111, -v140, v108, v111
	v_fma_f32 v110, -v149, v109, v110
	v_fma_f32 v111, -v141, v109, v111
	v_fma_f32 v111, -v142, v110, v111
	v_cndmask_b32_e32 v182, v108, v109, vcc
	v_cndmask_b32_e64 v182, v182, v110, s[4:5]
	v_cndmask_b32_e64 v182, v182, v111, s[6:7]
	v_mul_f32_e32 v182, v152, v182
	s_cmp_lt_u32 s0, 0x2b800000
	s_cbranch_scc0 .Lgdn_nomat_1_0
	v_pk_mul_f32 v[184:185], v[184:185], v[240:241] op_sel_hi:[1,0]
	v_pk_mul_f32 v[186:187], v[186:187], v[240:241] op_sel_hi:[1,0]
	v_pk_mul_f32 v[188:189], v[188:189], v[240:241] op_sel_hi:[1,0]
	v_pk_mul_f32 v[190:191], v[190:191], v[240:241] op_sel_hi:[1,0]
	v_pk_mul_f32 v[192:193], v[192:193], v[240:241] op_sel_hi:[1,0]
	v_pk_mul_f32 v[194:195], v[194:195], v[240:241] op_sel_hi:[1,0]
	v_pk_mul_f32 v[196:197], v[196:197], v[240:241] op_sel_hi:[1,0]
	v_pk_mul_f32 v[198:199], v[198:199], v[240:241] op_sel_hi:[1,0]
	v_pk_mul_f32 v[200:201], v[200:201], v[240:241] op_sel_hi:[1,0]
	v_pk_mul_f32 v[202:203], v[202:203], v[240:241] op_sel_hi:[1,0]
	v_pk_mul_f32 v[204:205], v[204:205], v[240:241] op_sel_hi:[1,0]
	v_pk_mul_f32 v[206:207], v[206:207], v[240:241] op_sel_hi:[1,0]
	v_pk_mul_f32 v[208:209], v[208:209], v[240:241] op_sel_hi:[1,0]
	v_pk_mul_f32 v[210:211], v[210:211], v[240:241] op_sel_hi:[1,0]
	v_pk_mul_f32 v[212:213], v[212:213], v[240:241] op_sel_hi:[1,0]
	v_pk_mul_f32 v[214:215], v[214:215], v[240:241] op_sel_hi:[1,0]
	v_mov_b32_e32 v240, 1.0
	v_mov_b32_e32 v89, 1.0

.Lgdn_nomat_1_1:
	v_mov_b32_e32 v238, v240
	v_mul_f32_e32 v90, v182, v89
	s_nop 1
	v_mfma_f32_16x16x4_f32 v[184:187], v62, v90, v[184:187]
	v_mfma_f32_16x16x4_f32 v[188:191], v63, v90, v[188:191]
	v_mfma_f32_16x16x4_f32 v[192:195], v64, v90, v[192:195]
	v_mfma_f32_16x16x4_f32 v[196:199], v65, v90, v[196:199]
	v_mfma_f32_16x16x4_f32 v[200:203], v66, v90, v[200:203]
	v_mfma_f32_16x16x4_f32 v[204:207], v67, v90, v[204:207]
	v_mfma_f32_16x16x4_f32 v[208:211], v68, v90, v[208:211]
	v_mfma_f32_16x16x4_f32 v[212:215], v69, v90, v[212:215]
	v_cndmask_b32_e32 v183, v82, v83, vcc
	v_cndmask_b32_e64 v183, v183, v84, s[4:5]
	v_cndmask_b32_e64 v183, v183, v85, s[6:7]
	v_mul_f32_e32 v179, v235, v183
	v_fmac_f32_e32 v179, v228, v108
	v_fmac_f32_e32 v179, v229, v109
	v_fmac_f32_e32 v179, v230, v110
	v_fmac_f32_e32 v179, v231, v111
	ds_write_b32 v172, v179 offset:3072
	v_add_u32_e32 v170, 0x1080, v170
	v_add_u32_e32 v237, 0x1080, v237
	v_add_u32_e32 v95, 0x1080, v95
	s_waitcnt lgkmcnt(1)
	v_mfma_f32_16x16x4_f32 v[96:99], v22, v184, 0
	v_mfma_f32_16x16x4_f32 v[100:103], v23, v185, 0
	v_mfma_f32_16x16x4_f32 v[96:99], v24, v186, v[96:99]
	v_mfma_f32_16x16x4_f32 v[100:103], v25, v187, v[100:103]
	v_mul_f32_e32 v129, v132, v70
	v_mul_f32_e32 v130, v133, v71
	v_mul_f32_e32 v131, v134, v72
	v_mul_f32_e32 v153, v135, v73
	v_mfma_f32_16x16x4_f32 v[96:99], v26, v188, v[96:99]
	v_mfma_f32_16x16x4_f32 v[100:103], v27, v189, v[100:103]
	v_mfma_f32_16x16x4_f32 v[96:99], v28, v190, v[96:99]
	v_mfma_f32_16x16x4_f32 v[100:103], v29, v191, v[100:103]
	v_mul_f32_e64 v114, -v132, v136
	v_mul_f32_e64 v115, -v133, v137
	v_mul_f32_e64 v116, -v134, v138
	v_mul_f32_e64 v117, -v135, v139
	v_mfma_f32_16x16x4_f32 v[96:99], v30, v192, v[96:99]
	v_mfma_f32_16x16x4_f32 v[100:103], v31, v193, v[100:103]
	v_mfma_f32_16x16x4_f32 v[96:99], v32, v194, v[96:99]
	v_mfma_f32_16x16x4_f32 v[100:103], v33, v195, v[100:103]
	v_mul_f32_e32 v240, v238, v139
	v_rcp_f32_e32 v89, v240
	v_readfirstlane_b32 s0, v240
	ds_read_b32 v86, v87 offset:1024
	v_mfma_f32_16x16x4_f32 v[96:99], v34, v196, v[96:99]
	v_mfma_f32_16x16x4_f32 v[100:103], v35, v197, v[100:103]
	v_mfma_f32_16x16x4_f32 v[96:99], v36, v198, v[96:99]
	v_mfma_f32_16x16x4_f32 v[100:103], v37, v199, v[100:103]
	ds_read2_b32 v[62:63], v237 offset0:0 offset1:16
	ds_read2_b32 v[64:65], v237 offset0:32 offset1:48
	ds_read2_b32 v[66:67], v237 offset0:64 offset1:80
	ds_read2_b32 v[68:69], v237 offset0:96 offset1:112
	v_mfma_f32_16x16x4_f32 v[96:99], v38, v200, v[96:99]
	v_mfma_f32_16x16x4_f32 v[100:103], v39, v201, v[100:103]
	v_mfma_f32_16x16x4_f32 v[96:99], v40, v202, v[96:99]
	v_mfma_f32_16x16x4_f32 v[100:103], v41, v203, v[100:103]
	ds_read2st64_b32 v[74:75], v171 offset0:20 offset1:21
	ds_read2st64_b32 v[76:77], v171 offset0:22 offset1:23
	ds_read_b128 v[216:219], v175 offset:80
	ds_read_b128 v[220:223], v175 offset:336
	v_mfma_f32_16x16x4_f32 v[96:99], v42, v204, v[96:99]
	v_mfma_f32_16x16x4_f32 v[100:103], v43, v205, v[100:103]
	v_mfma_f32_16x16x4_f32 v[96:99], v44, v206, v[96:99]
	v_mfma_f32_16x16x4_f32 v[100:103], v45, v207, v[100:103]
	ds_read_b32 v235, v176 offset:336
	ds_read_b32 v236, v176 offset:592
	ds_read_b32 v234, v173 offset:1200
	ds_read_b64 v[232:233], v173 offset:1232
	v_mfma_f32_16x16x4_f32 v[96:99], v46, v208, v[96:99]
	v_mfma_f32_16x16x4_f32 v[100:103], v47, v209, v[100:103]
	v_mfma_f32_16x16x4_f32 v[96:99], v48, v210, v[96:99]
	v_mfma_f32_16x16x4_f32 v[100:103], v49, v211, v[100:103]
	ds_read_b128 v[224:227], v173 offset:1264
	ds_read_b128 v[228:231], v174 offset:1168
	v_mfma_f32_16x16x4_f32 v[96:99], v50, v212, v[96:99]
	v_mfma_f32_16x16x4_f32 v[100:103], v51, v213, v[100:103]
	v_mfma_f32_16x16x4_f32 v[96:99], v52, v214, v[96:99]
	v_mfma_f32_16x16x4_f32 v[100:103], v53, v215, v[100:103]
	s_nop 7
	s_nop 1
	v_pk_mul_f32 v[100:101], v[100:101], v[238:239] op_sel_hi:[1,0]
	v_pk_mul_f32 v[102:103], v[102:103], v[238:239] op_sel_hi:[1,0]
	v_pk_fma_f32 v[78:79], v[96:97], v[238:239], v[100:101] op_sel_hi:[1,0,1]
	v_pk_fma_f32 v[80:81], v[98:99], v[238:239], v[102:103] op_sel_hi:[1,0,1]
	v_pk_fma_f32 v[96:97], v[96:97], v[238:239], v[100:101] op_sel_hi:[1,0,1]
	v_pk_fma_f32 v[98:99], v[98:99], v[238:239], v[102:103] op_sel_hi:[1,0,1]
	s_nop 0
	v_permlane32_swap_b32_e32 v96, v78
	v_permlane32_swap_b32_e32 v97, v79
	v_permlane32_swap_b32_e32 v98, v80
	v_permlane32_swap_b32_e32 v99, v81
	v_mov_b32_e32 v82, v96
	v_mov_b32_e32 v83, v97
	v_mov_b32_e32 v84, v98
	v_mov_b32_e32 v85, v99
	s_nop 0
	v_permlane16_swap_b32_e32 v96, v82
	v_permlane16_swap_b32_e32 v97, v83
	v_permlane16_swap_b32_e32 v98, v84
	v_permlane16_swap_b32_e32 v99, v85
	v_fma_f32 v108, v114, v96, v129
	v_fma_f32 v109, v115, v97, v130
	v_fma_f32 v110, v116, v98, v131
	v_fma_f32 v111, v117, v99, v153
	v_fma_f32 v109, -v150, v108, v109
	v_fma_f32 v110, -v148, v108, v110
	v_fma_f32 v111, -v140, v108, v111
	v_fma_f32 v110, -v149, v109, v110
	v_fma_f32 v111, -v141, v109, v111
	v_fma_f32 v111, -v142, v110, v111
	v_cndmask_b32_e32 v182, v108, v109, vcc
	v_cndmask_b32_e64 v182, v182, v110, s[4:5]
	v_cndmask_b32_e64 v182, v182, v111, s[6:7]
	v_mul_f32_e32 v182, v152, v182
	s_cmp_lt_u32 s0, 0x2b800000
	s_cbranch_scc0 .Lgdn_nomat_2_0
	v_pk_mul_f32 v[184:185], v[184:185], v[240:241] op_sel_hi:[1,0]
	v_pk_mul_f32 v[186:187], v[186:187], v[240:241] op_sel_hi:[1,0]
	v_pk_mul_f32 v[188:189], v[188:189], v[240:241] op_sel_hi:[1,0]
	v_pk_mul_f32 v[190:191], v[190:191], v[240:241] op_sel_hi:[1,0]
	v_pk_mul_f32 v[192:193], v[192:193], v[240:241] op_sel_hi:[1,0]
	v_pk_mul_f32 v[194:195], v[194:195], v[240:241] op_sel_hi:[1,0]
	v_pk_mul_f32 v[196:197], v[196:197], v[240:241] op_sel_hi:[1,0]
	v_pk_mul_f32 v[198:199], v[198:199], v[240:241] op_sel_hi:[1,0]
	v_pk_mul_f32 v[200:201], v[200:201], v[240:241] op_sel_hi:[1,0]
	v_pk_mul_f32 v[202:203], v[202:203], v[240:241] op_sel_hi:[1,0]
	v_pk_mul_f32 v[204:205], v[204:205], v[240:241] op_sel_hi:[1,0]
	v_pk_mul_f32 v[206:207], v[206:207], v[240:241] op_sel_hi:[1,0]
	v_pk_mul_f32 v[208:209], v[208:209], v[240:241] op_sel_hi:[1,0]
	v_pk_mul_f32 v[210:211], v[210:211], v[240:241] op_sel_hi:[1,0]
	v_pk_mul_f32 v[212:213], v[212:213], v[240:241] op_sel_hi:[1,0]
	v_pk_mul_f32 v[214:215], v[214:215], v[240:241] op_sel_hi:[1,0]
	v_mov_b32_e32 v240, 1.0
	v_mov_b32_e32 v89, 1.0

.Lgdn_nomat_2_1:
	v_mov_b32_e32 v238, v240
	v_mul_f32_e32 v90, v182, v89
	s_nop 1
	v_mfma_f32_16x16x4_f32 v[184:187], v62, v90, v[184:187]
	v_mfma_f32_16x16x4_f32 v[188:191], v63, v90, v[188:191]
	v_mfma_f32_16x16x4_f32 v[192:195], v64, v90, v[192:195]
	v_mfma_f32_16x16x4_f32 v[196:199], v65, v90, v[196:199]
	v_mfma_f32_16x16x4_f32 v[200:203], v66, v90, v[200:203]
	v_mfma_f32_16x16x4_f32 v[204:207], v67, v90, v[204:207]
	v_mfma_f32_16x16x4_f32 v[208:211], v68, v90, v[208:211]
	v_mfma_f32_16x16x4_f32 v[212:215], v69, v90, v[212:215]
	v_cndmask_b32_e32 v183, v82, v83, vcc
	v_cndmask_b32_e64 v183, v183, v84, s[4:5]
	v_cndmask_b32_e64 v183, v183, v85, s[6:7]
	v_mul_f32_e32 v179, v235, v183
	v_fmac_f32_e32 v179, v228, v108
	v_fmac_f32_e32 v179, v229, v109
	v_fmac_f32_e32 v179, v230, v110
	v_fmac_f32_e32 v179, v231, v111
	ds_write_b32 v172, v179 offset:5120
	v_add_u32_e32 v170, 0x1080, v170
	v_add_u32_e32 v237, 0x1080, v237
	v_add_u32_e32 v95, 0x1080, v95
	s_waitcnt lgkmcnt(1)
	v_mfma_f32_16x16x4_f32 v[96:99], v22, v184, 0
	v_mfma_f32_16x16x4_f32 v[100:103], v23, v185, 0
	v_mfma_f32_16x16x4_f32 v[96:99], v24, v186, v[96:99]
	v_mfma_f32_16x16x4_f32 v[100:103], v25, v187, v[100:103]
	v_mul_f32_e32 v129, v132, v70
	v_mul_f32_e32 v130, v133, v71
	v_mul_f32_e32 v131, v134, v72
	v_mul_f32_e32 v153, v135, v73
	v_mfma_f32_16x16x4_f32 v[96:99], v26, v188, v[96:99]
	v_mfma_f32_16x16x4_f32 v[100:103], v27, v189, v[100:103]
	v_mfma_f32_16x16x4_f32 v[96:99], v28, v190, v[96:99]
	v_mfma_f32_16x16x4_f32 v[100:103], v29, v191, v[100:103]
	v_mul_f32_e64 v114, -v132, v136
	v_mul_f32_e64 v115, -v133, v137
	v_mul_f32_e64 v116, -v134, v138
	v_mul_f32_e64 v117, -v135, v139
	v_mfma_f32_16x16x4_f32 v[96:99], v30, v192, v[96:99]
	v_mfma_f32_16x16x4_f32 v[100:103], v31, v193, v[100:103]
	v_mfma_f32_16x16x4_f32 v[96:99], v32, v194, v[96:99]
	v_mfma_f32_16x16x4_f32 v[100:103], v33, v195, v[100:103]
	v_mul_f32_e32 v240, v238, v139
	v_rcp_f32_e32 v89, v240
	v_readfirstlane_b32 s0, v240
	ds_read_b32 v86, v87 offset:1536
	v_mfma_f32_16x16x4_f32 v[96:99], v34, v196, v[96:99]
	v_mfma_f32_16x16x4_f32 v[100:103], v35, v197, v[100:103]
	v_mfma_f32_16x16x4_f32 v[96:99], v36, v198, v[96:99]
	v_mfma_f32_16x16x4_f32 v[100:103], v37, v199, v[100:103]
	ds_read2_b32 v[62:63], v237 offset0:0 offset1:16
	ds_read2_b32 v[64:65], v237 offset0:32 offset1:48
	ds_read2_b32 v[66:67], v237 offset0:64 offset1:80
	ds_read2_b32 v[68:69], v237 offset0:96 offset1:112
	v_mfma_f32_16x16x4_f32 v[96:99], v38, v200, v[96:99]
	v_mfma_f32_16x16x4_f32 v[100:103], v39, v201, v[100:103]
	v_mfma_f32_16x16x4_f32 v[96:99], v40, v202, v[96:99]
	v_mfma_f32_16x16x4_f32 v[100:103], v41, v203, v[100:103]
	ds_read2st64_b32 v[74:75], v171 offset0:28 offset1:29
	ds_read2st64_b32 v[76:77], v171 offset0:30 offset1:31
	ds_read_b128 v[216:219], v175 offset:112
	ds_read_b128 v[220:223], v175 offset:368
	v_mfma_f32_16x16x4_f32 v[96:99], v42, v204, v[96:99]
	v_mfma_f32_16x16x4_f32 v[100:103], v43, v205, v[100:103]
	v_mfma_f32_16x16x4_f32 v[96:99], v44, v206, v[96:99]
	v_mfma_f32_16x16x4_f32 v[100:103], v45, v207, v[100:103]
	ds_read_b32 v235, v176 offset:368
	ds_read_b32 v236, v176 offset:624
	ds_read_b32 v234, v173 offset:1712
	ds_read_b64 v[232:233], v173 offset:1744
	v_mfma_f32_16x16x4_f32 v[96:99], v46, v208, v[96:99]
	v_mfma_f32_16x16x4_f32 v[100:103], v47, v209, v[100:103]
	v_mfma_f32_16x16x4_f32 v[96:99], v48, v210, v[96:99]
	v_mfma_f32_16x16x4_f32 v[100:103], v49, v211, v[100:103]
	ds_read_b128 v[224:227], v173 offset:1776
	ds_read_b128 v[228:231], v174 offset:1680
	v_mfma_f32_16x16x4_f32 v[96:99], v50, v212, v[96:99]
	v_mfma_f32_16x16x4_f32 v[100:103], v51, v213, v[100:103]
	v_mfma_f32_16x16x4_f32 v[96:99], v52, v214, v[96:99]
	v_mfma_f32_16x16x4_f32 v[100:103], v53, v215, v[100:103]
	s_nop 7
	s_nop 1
	v_pk_mul_f32 v[100:101], v[100:101], v[238:239] op_sel_hi:[1,0]
	v_pk_mul_f32 v[102:103], v[102:103], v[238:239] op_sel_hi:[1,0]
	v_pk_fma_f32 v[78:79], v[96:97], v[238:239], v[100:101] op_sel_hi:[1,0,1]
	v_pk_fma_f32 v[80:81], v[98:99], v[238:239], v[102:103] op_sel_hi:[1,0,1]
	v_pk_fma_f32 v[96:97], v[96:97], v[238:239], v[100:101] op_sel_hi:[1,0,1]
	v_pk_fma_f32 v[98:99], v[98:99], v[238:239], v[102:103] op_sel_hi:[1,0,1]
	s_nop 0
	v_permlane32_swap_b32_e32 v96, v78
	v_permlane32_swap_b32_e32 v97, v79
	v_permlane32_swap_b32_e32 v98, v80
	v_permlane32_swap_b32_e32 v99, v81
	v_mov_b32_e32 v82, v96
	v_mov_b32_e32 v83, v97
	v_mov_b32_e32 v84, v98
	v_mov_b32_e32 v85, v99
	s_nop 0
	v_permlane16_swap_b32_e32 v96, v82
	v_permlane16_swap_b32_e32 v97, v83
	v_permlane16_swap_b32_e32 v98, v84
	v_permlane16_swap_b32_e32 v99, v85
	v_fma_f32 v108, v114, v96, v129
	v_fma_f32 v109, v115, v97, v130
	v_fma_f32 v110, v116, v98, v131
	v_fma_f32 v111, v117, v99, v153
	v_fma_f32 v109, -v150, v108, v109
	v_fma_f32 v110, -v148, v108, v110
	v_fma_f32 v111, -v140, v108, v111
	v_fma_f32 v110, -v149, v109, v110
	v_fma_f32 v111, -v141, v109, v111
	v_fma_f32 v111, -v142, v110, v111
	v_cndmask_b32_e32 v182, v108, v109, vcc
	v_cndmask_b32_e64 v182, v182, v110, s[4:5]
	v_cndmask_b32_e64 v182, v182, v111, s[6:7]
	v_mul_f32_e32 v182, v152, v182
	s_cmp_lt_u32 s0, 0x2b800000
	s_cbranch_scc0 .Lgdn_nomat_3_0
	v_pk_mul_f32 v[184:185], v[184:185], v[240:241] op_sel_hi:[1,0]
	v_pk_mul_f32 v[186:187], v[186:187], v[240:241] op_sel_hi:[1,0]
	v_pk_mul_f32 v[188:189], v[188:189], v[240:241] op_sel_hi:[1,0]
	v_pk_mul_f32 v[190:191], v[190:191], v[240:241] op_sel_hi:[1,0]
	v_pk_mul_f32 v[192:193], v[192:193], v[240:241] op_sel_hi:[1,0]
	v_pk_mul_f32 v[194:195], v[194:195], v[240:241] op_sel_hi:[1,0]
	v_pk_mul_f32 v[196:197], v[196:197], v[240:241] op_sel_hi:[1,0]
	v_pk_mul_f32 v[198:199], v[198:199], v[240:241] op_sel_hi:[1,0]
	v_pk_mul_f32 v[200:201], v[200:201], v[240:241] op_sel_hi:[1,0]
	v_pk_mul_f32 v[202:203], v[202:203], v[240:241] op_sel_hi:[1,0]
	v_pk_mul_f32 v[204:205], v[204:205], v[240:241] op_sel_hi:[1,0]
	v_pk_mul_f32 v[206:207], v[206:207], v[240:241] op_sel_hi:[1,0]
	v_pk_mul_f32 v[208:209], v[208:209], v[240:241] op_sel_hi:[1,0]
	v_pk_mul_f32 v[210:211], v[210:211], v[240:241] op_sel_hi:[1,0]
	v_pk_mul_f32 v[212:213], v[212:213], v[240:241] op_sel_hi:[1,0]
	v_pk_mul_f32 v[214:215], v[214:215], v[240:241] op_sel_hi:[1,0]
	v_mov_b32_e32 v240, 1.0
	v_mov_b32_e32 v89, 1.0

.Lgdn_nomat_3_1:
	v_mov_b32_e32 v238, v240
	v_mul_f32_e32 v90, v182, v89
	s_nop 1
	v_mfma_f32_16x16x4_f32 v[184:187], v62, v90, v[184:187]
	v_mfma_f32_16x16x4_f32 v[188:191], v63, v90, v[188:191]
	v_mfma_f32_16x16x4_f32 v[192:195], v64, v90, v[192:195]
	v_mfma_f32_16x16x4_f32 v[196:199], v65, v90, v[196:199]
	v_mfma_f32_16x16x4_f32 v[200:203], v66, v90, v[200:203]
	v_mfma_f32_16x16x4_f32 v[204:207], v67, v90, v[204:207]
	v_mfma_f32_16x16x4_f32 v[208:211], v68, v90, v[208:211]
	v_mfma_f32_16x16x4_f32 v[212:215], v69, v90, v[212:215]
	v_cndmask_b32_e32 v183, v82, v83, vcc
	v_cndmask_b32_e64 v183, v183, v84, s[4:5]
	v_cndmask_b32_e64 v183, v183, v85, s[6:7]
	v_mul_f32_e32 v179, v235, v183
	v_fmac_f32_e32 v179, v228, v108
	v_fmac_f32_e32 v179, v229, v109
	v_fmac_f32_e32 v179, v230, v110
	v_fmac_f32_e32 v179, v231, v111
	ds_write_b32 v172, v179 offset:7168
	v_add_u32_e32 v170, 0x1080, v170
	v_add_u32_e32 v237, 0x1080, v237
	v_add_u32_e32 v95, 0x1080, v95
	s_waitcnt lgkmcnt(1)
	v_mfma_f32_16x16x4_f32 v[96:99], v22, v184, 0
	v_mfma_f32_16x16x4_f32 v[100:103], v23, v185, 0
	v_mfma_f32_16x16x4_f32 v[96:99], v24, v186, v[96:99]
	v_mfma_f32_16x16x4_f32 v[100:103], v25, v187, v[100:103]
	v_mul_f32_e32 v129, v132, v70
	v_mul_f32_e32 v130, v133, v71
	v_mul_f32_e32 v131, v134, v72
	v_mul_f32_e32 v153, v135, v73
	v_mfma_f32_16x16x4_f32 v[96:99], v26, v188, v[96:99]
	v_mfma_f32_16x16x4_f32 v[100:103], v27, v189, v[100:103]
	v_mfma_f32_16x16x4_f32 v[96:99], v28, v190, v[96:99]
	v_mfma_f32_16x16x4_f32 v[100:103], v29, v191, v[100:103]
	v_mul_f32_e64 v114, -v132, v136
	v_mul_f32_e64 v115, -v133, v137
	v_mul_f32_e64 v116, -v134, v138
	v_mul_f32_e64 v117, -v135, v139
	v_mfma_f32_16x16x4_f32 v[96:99], v30, v192, v[96:99]
	v_mfma_f32_16x16x4_f32 v[100:103], v31, v193, v[100:103]
	v_mfma_f32_16x16x4_f32 v[96:99], v32, v194, v[96:99]
	v_mfma_f32_16x16x4_f32 v[100:103], v33, v195, v[100:103]
	v_mul_f32_e32 v240, v238, v139
	v_rcp_f32_e32 v89, v240
	v_readfirstlane_b32 s0, v240
	ds_read_b32 v86, v87 offset:2048
	v_mfma_f32_16x16x4_f32 v[96:99], v34, v196, v[96:99]
	v_mfma_f32_16x16x4_f32 v[100:103], v35, v197, v[100:103]
	v_mfma_f32_16x16x4_f32 v[96:99], v36, v198, v[96:99]
	v_mfma_f32_16x16x4_f32 v[100:103], v37, v199, v[100:103]
	ds_read2_b32 v[62:63], v237 offset0:0 offset1:16
	ds_read2_b32 v[64:65], v237 offset0:32 offset1:48
	ds_read2_b32 v[66:67], v237 offset0:64 offset1:80
	ds_read2_b32 v[68:69], v237 offset0:96 offset1:112
	v_mfma_f32_16x16x4_f32 v[96:99], v38, v200, v[96:99]
	v_mfma_f32_16x16x4_f32 v[100:103], v39, v201, v[100:103]
	v_mfma_f32_16x16x4_f32 v[96:99], v40, v202, v[96:99]
	v_mfma_f32_16x16x4_f32 v[100:103], v41, v203, v[100:103]
	ds_read2st64_b32 v[74:75], v171 offset0:36 offset1:37
	ds_read2st64_b32 v[76:77], v171 offset0:38 offset1:39
	ds_read_b128 v[216:219], v175 offset:144
	ds_read_b128 v[220:223], v175 offset:400
	v_mfma_f32_16x16x4_f32 v[96:99], v42, v204, v[96:99]
	v_mfma_f32_16x16x4_f32 v[100:103], v43, v205, v[100:103]
	v_mfma_f32_16x16x4_f32 v[96:99], v44, v206, v[96:99]
	v_mfma_f32_16x16x4_f32 v[100:103], v45, v207, v[100:103]
	ds_read_b32 v235, v176 offset:400
	ds_read_b32 v236, v176 offset:656
	ds_read_b32 v234, v173 offset:2224
	ds_read_b64 v[232:233], v173 offset:2256
	v_mfma_f32_16x16x4_f32 v[96:99], v46, v208, v[96:99]
	v_mfma_f32_16x16x4_f32 v[100:103], v47, v209, v[100:103]
	v_mfma_f32_16x16x4_f32 v[96:99], v48, v210, v[96:99]
	v_mfma_f32_16x16x4_f32 v[100:103], v49, v211, v[100:103]
	ds_read_b128 v[224:227], v173 offset:2288
	ds_read_b128 v[228:231], v174 offset:2192
	v_mfma_f32_16x16x4_f32 v[96:99], v50, v212, v[96:99]
	v_mfma_f32_16x16x4_f32 v[100:103], v51, v213, v[100:103]
	v_mfma_f32_16x16x4_f32 v[96:99], v52, v214, v[96:99]
	v_mfma_f32_16x16x4_f32 v[100:103], v53, v215, v[100:103]
	s_nop 7
	s_nop 1
	v_pk_mul_f32 v[100:101], v[100:101], v[238:239] op_sel_hi:[1,0]
	v_pk_mul_f32 v[102:103], v[102:103], v[238:239] op_sel_hi:[1,0]
	v_pk_fma_f32 v[78:79], v[96:97], v[238:239], v[100:101] op_sel_hi:[1,0,1]
	v_pk_fma_f32 v[80:81], v[98:99], v[238:239], v[102:103] op_sel_hi:[1,0,1]
	v_pk_fma_f32 v[96:97], v[96:97], v[238:239], v[100:101] op_sel_hi:[1,0,1]
	v_pk_fma_f32 v[98:99], v[98:99], v[238:239], v[102:103] op_sel_hi:[1,0,1]
	s_nop 0
	v_permlane32_swap_b32_e32 v96, v78
	v_permlane32_swap_b32_e32 v97, v79
	v_permlane32_swap_b32_e32 v98, v80
	v_permlane32_swap_b32_e32 v99, v81
	v_mov_b32_e32 v82, v96
	v_mov_b32_e32 v83, v97
	v_mov_b32_e32 v84, v98
	v_mov_b32_e32 v85, v99
	s_nop 0
	v_permlane16_swap_b32_e32 v96, v82
	v_permlane16_swap_b32_e32 v97, v83
	v_permlane16_swap_b32_e32 v98, v84
	v_permlane16_swap_b32_e32 v99, v85
	v_fma_f32 v108, v114, v96, v129
	v_fma_f32 v109, v115, v97, v130
	v_fma_f32 v110, v116, v98, v131
	v_fma_f32 v111, v117, v99, v153
	v_fma_f32 v109, -v150, v108, v109
	v_fma_f32 v110, -v148, v108, v110
	v_fma_f32 v111, -v140, v108, v111
	v_fma_f32 v110, -v149, v109, v110
	v_fma_f32 v111, -v141, v109, v111
	v_fma_f32 v111, -v142, v110, v111
	v_cndmask_b32_e32 v182, v108, v109, vcc
	v_cndmask_b32_e64 v182, v182, v110, s[4:5]
	v_cndmask_b32_e64 v182, v182, v111, s[6:7]
	v_mul_f32_e32 v182, v152, v182
	s_cmp_lt_u32 s0, 0x2b800000
	s_cbranch_scc0 .Lgdn_nomat_4_0
	v_pk_mul_f32 v[184:185], v[184:185], v[240:241] op_sel_hi:[1,0]
	v_pk_mul_f32 v[186:187], v[186:187], v[240:241] op_sel_hi:[1,0]
	v_pk_mul_f32 v[188:189], v[188:189], v[240:241] op_sel_hi:[1,0]
	v_pk_mul_f32 v[190:191], v[190:191], v[240:241] op_sel_hi:[1,0]
	v_pk_mul_f32 v[192:193], v[192:193], v[240:241] op_sel_hi:[1,0]
	v_pk_mul_f32 v[194:195], v[194:195], v[240:241] op_sel_hi:[1,0]
	v_pk_mul_f32 v[196:197], v[196:197], v[240:241] op_sel_hi:[1,0]
	v_pk_mul_f32 v[198:199], v[198:199], v[240:241] op_sel_hi:[1,0]
	v_pk_mul_f32 v[200:201], v[200:201], v[240:241] op_sel_hi:[1,0]
	v_pk_mul_f32 v[202:203], v[202:203], v[240:241] op_sel_hi:[1,0]
	v_pk_mul_f32 v[204:205], v[204:205], v[240:241] op_sel_hi:[1,0]
	v_pk_mul_f32 v[206:207], v[206:207], v[240:241] op_sel_hi:[1,0]
	v_pk_mul_f32 v[208:209], v[208:209], v[240:241] op_sel_hi:[1,0]
	v_pk_mul_f32 v[210:211], v[210:211], v[240:241] op_sel_hi:[1,0]
	v_pk_mul_f32 v[212:213], v[212:213], v[240:241] op_sel_hi:[1,0]
	v_pk_mul_f32 v[214:215], v[214:215], v[240:241] op_sel_hi:[1,0]
	v_mov_b32_e32 v240, 1.0
	v_mov_b32_e32 v89, 1.0

.Lgdn_nomat_4_1:
	v_mov_b32_e32 v238, v240
	v_mul_f32_e32 v90, v182, v89
	s_nop 1
	v_mfma_f32_16x16x4_f32 v[184:187], v62, v90, v[184:187]
	v_mfma_f32_16x16x4_f32 v[188:191], v63, v90, v[188:191]
	v_mfma_f32_16x16x4_f32 v[192:195], v64, v90, v[192:195]
	v_mfma_f32_16x16x4_f32 v[196:199], v65, v90, v[196:199]
	v_mfma_f32_16x16x4_f32 v[200:203], v66, v90, v[200:203]
	v_mfma_f32_16x16x4_f32 v[204:207], v67, v90, v[204:207]
	v_mfma_f32_16x16x4_f32 v[208:211], v68, v90, v[208:211]
	v_mfma_f32_16x16x4_f32 v[212:215], v69, v90, v[212:215]
	v_cndmask_b32_e32 v183, v82, v83, vcc
	v_cndmask_b32_e64 v183, v183, v84, s[4:5]
	v_cndmask_b32_e64 v183, v183, v85, s[6:7]
	v_mul_f32_e32 v179, v235, v183
	v_fmac_f32_e32 v179, v228, v108
	v_fmac_f32_e32 v179, v229, v109
	v_fmac_f32_e32 v179, v230, v110
	v_fmac_f32_e32 v179, v231, v111
	ds_write_b32 v172, v179 offset:9216
	v_add_u32_e32 v170, 0x1080, v170
	v_add_u32_e32 v237, 0x1080, v237
	v_add_u32_e32 v95, 0x1080, v95
	s_waitcnt lgkmcnt(1)
	v_mfma_f32_16x16x4_f32 v[96:99], v22, v184, 0
	v_mfma_f32_16x16x4_f32 v[100:103], v23, v185, 0
	v_mfma_f32_16x16x4_f32 v[96:99], v24, v186, v[96:99]
	v_mfma_f32_16x16x4_f32 v[100:103], v25, v187, v[100:103]
	v_mul_f32_e32 v129, v132, v70
	v_mul_f32_e32 v130, v133, v71
	v_mul_f32_e32 v131, v134, v72
	v_mul_f32_e32 v153, v135, v73
	v_mfma_f32_16x16x4_f32 v[96:99], v26, v188, v[96:99]
	v_mfma_f32_16x16x4_f32 v[100:103], v27, v189, v[100:103]
	v_mfma_f32_16x16x4_f32 v[96:99], v28, v190, v[96:99]
	v_mfma_f32_16x16x4_f32 v[100:103], v29, v191, v[100:103]
	v_mul_f32_e64 v114, -v132, v136
	v_mul_f32_e64 v115, -v133, v137
	v_mul_f32_e64 v116, -v134, v138
	v_mul_f32_e64 v117, -v135, v139
	v_mfma_f32_16x16x4_f32 v[96:99], v30, v192, v[96:99]
	v_mfma_f32_16x16x4_f32 v[100:103], v31, v193, v[100:103]
	v_mfma_f32_16x16x4_f32 v[96:99], v32, v194, v[96:99]
	v_mfma_f32_16x16x4_f32 v[100:103], v33, v195, v[100:103]
	v_mul_f32_e32 v240, v238, v139
	v_rcp_f32_e32 v89, v240
	v_readfirstlane_b32 s0, v240
	ds_read_b32 v86, v87 offset:2560
	v_mfma_f32_16x16x4_f32 v[96:99], v34, v196, v[96:99]
	v_mfma_f32_16x16x4_f32 v[100:103], v35, v197, v[100:103]
	v_mfma_f32_16x16x4_f32 v[96:99], v36, v198, v[96:99]
	v_mfma_f32_16x16x4_f32 v[100:103], v37, v199, v[100:103]
	ds_read2_b32 v[62:63], v237 offset0:0 offset1:16
	ds_read2_b32 v[64:65], v237 offset0:32 offset1:48
	ds_read2_b32 v[66:67], v237 offset0:64 offset1:80
	ds_read2_b32 v[68:69], v237 offset0:96 offset1:112
	v_mfma_f32_16x16x4_f32 v[96:99], v38, v200, v[96:99]
	v_mfma_f32_16x16x4_f32 v[100:103], v39, v201, v[100:103]
	v_mfma_f32_16x16x4_f32 v[96:99], v40, v202, v[96:99]
	v_mfma_f32_16x16x4_f32 v[100:103], v41, v203, v[100:103]
	ds_read2st64_b32 v[74:75], v171 offset0:44 offset1:45
	ds_read2st64_b32 v[76:77], v171 offset0:46 offset1:47
	ds_read_b128 v[216:219], v175 offset:176
	ds_read_b128 v[220:223], v175 offset:432
	v_mfma_f32_16x16x4_f32 v[96:99], v42, v204, v[96:99]
	v_mfma_f32_16x16x4_f32 v[100:103], v43, v205, v[100:103]
	v_mfma_f32_16x16x4_f32 v[96:99], v44, v206, v[96:99]
	v_mfma_f32_16x16x4_f32 v[100:103], v45, v207, v[100:103]
	ds_read_b32 v235, v176 offset:432
	ds_read_b32 v236, v176 offset:688
	ds_read_b32 v234, v173 offset:2736
	ds_read_b64 v[232:233], v173 offset:2768
	v_mfma_f32_16x16x4_f32 v[96:99], v46, v208, v[96:99]
	v_mfma_f32_16x16x4_f32 v[100:103], v47, v209, v[100:103]
	v_mfma_f32_16x16x4_f32 v[96:99], v48, v210, v[96:99]
	v_mfma_f32_16x16x4_f32 v[100:103], v49, v211, v[100:103]
	ds_read_b128 v[224:227], v173 offset:2800
	ds_read_b128 v[228:231], v174 offset:2704
	v_mfma_f32_16x16x4_f32 v[96:99], v50, v212, v[96:99]
	v_mfma_f32_16x16x4_f32 v[100:103], v51, v213, v[100:103]
	v_mfma_f32_16x16x4_f32 v[96:99], v52, v214, v[96:99]
	v_mfma_f32_16x16x4_f32 v[100:103], v53, v215, v[100:103]
	s_nop 7
	s_nop 1
	v_pk_mul_f32 v[100:101], v[100:101], v[238:239] op_sel_hi:[1,0]
	v_pk_mul_f32 v[102:103], v[102:103], v[238:239] op_sel_hi:[1,0]
	v_pk_fma_f32 v[78:79], v[96:97], v[238:239], v[100:101] op_sel_hi:[1,0,1]
	v_pk_fma_f32 v[80:81], v[98:99], v[238:239], v[102:103] op_sel_hi:[1,0,1]
	v_pk_fma_f32 v[96:97], v[96:97], v[238:239], v[100:101] op_sel_hi:[1,0,1]
	v_pk_fma_f32 v[98:99], v[98:99], v[238:239], v[102:103] op_sel_hi:[1,0,1]
	s_nop 0
	v_permlane32_swap_b32_e32 v96, v78
	v_permlane32_swap_b32_e32 v97, v79
	v_permlane32_swap_b32_e32 v98, v80
	v_permlane32_swap_b32_e32 v99, v81
	v_mov_b32_e32 v82, v96
	v_mov_b32_e32 v83, v97
	v_mov_b32_e32 v84, v98
	v_mov_b32_e32 v85, v99
	s_nop 0
	v_permlane16_swap_b32_e32 v96, v82
	v_permlane16_swap_b32_e32 v97, v83
	v_permlane16_swap_b32_e32 v98, v84
	v_permlane16_swap_b32_e32 v99, v85
	v_fma_f32 v108, v114, v96, v129
	v_fma_f32 v109, v115, v97, v130
	v_fma_f32 v110, v116, v98, v131
	v_fma_f32 v111, v117, v99, v153
	v_fma_f32 v109, -v150, v108, v109
	v_fma_f32 v110, -v148, v108, v110
	v_fma_f32 v111, -v140, v108, v111
	v_fma_f32 v110, -v149, v109, v110
	v_fma_f32 v111, -v141, v109, v111
	v_fma_f32 v111, -v142, v110, v111
	v_cndmask_b32_e32 v182, v108, v109, vcc
	v_cndmask_b32_e64 v182, v182, v110, s[4:5]
	v_cndmask_b32_e64 v182, v182, v111, s[6:7]
	v_mul_f32_e32 v182, v152, v182
	s_cmp_lt_u32 s0, 0x2b800000
	s_cbranch_scc0 .Lgdn_nomat_5_0
	v_pk_mul_f32 v[184:185], v[184:185], v[240:241] op_sel_hi:[1,0]
	v_pk_mul_f32 v[186:187], v[186:187], v[240:241] op_sel_hi:[1,0]
	v_pk_mul_f32 v[188:189], v[188:189], v[240:241] op_sel_hi:[1,0]
	v_pk_mul_f32 v[190:191], v[190:191], v[240:241] op_sel_hi:[1,0]
	v_pk_mul_f32 v[192:193], v[192:193], v[240:241] op_sel_hi:[1,0]
	v_pk_mul_f32 v[194:195], v[194:195], v[240:241] op_sel_hi:[1,0]
	v_pk_mul_f32 v[196:197], v[196:197], v[240:241] op_sel_hi:[1,0]
	v_pk_mul_f32 v[198:199], v[198:199], v[240:241] op_sel_hi:[1,0]
	v_pk_mul_f32 v[200:201], v[200:201], v[240:241] op_sel_hi:[1,0]
	v_pk_mul_f32 v[202:203], v[202:203], v[240:241] op_sel_hi:[1,0]
	v_pk_mul_f32 v[204:205], v[204:205], v[240:241] op_sel_hi:[1,0]
	v_pk_mul_f32 v[206:207], v[206:207], v[240:241] op_sel_hi:[1,0]
	v_pk_mul_f32 v[208:209], v[208:209], v[240:241] op_sel_hi:[1,0]
	v_pk_mul_f32 v[210:211], v[210:211], v[240:241] op_sel_hi:[1,0]
	v_pk_mul_f32 v[212:213], v[212:213], v[240:241] op_sel_hi:[1,0]
	v_pk_mul_f32 v[214:215], v[214:215], v[240:241] op_sel_hi:[1,0]
	v_mov_b32_e32 v240, 1.0
	v_mov_b32_e32 v89, 1.0

.Lgdn_nomat_5_1:
	v_mov_b32_e32 v238, v240
	v_mul_f32_e32 v90, v182, v89
	s_nop 1
	v_mfma_f32_16x16x4_f32 v[184:187], v62, v90, v[184:187]
	v_mfma_f32_16x16x4_f32 v[188:191], v63, v90, v[188:191]
	v_mfma_f32_16x16x4_f32 v[192:195], v64, v90, v[192:195]
	v_mfma_f32_16x16x4_f32 v[196:199], v65, v90, v[196:199]
	v_mfma_f32_16x16x4_f32 v[200:203], v66, v90, v[200:203]
	v_mfma_f32_16x16x4_f32 v[204:207], v67, v90, v[204:207]
	v_mfma_f32_16x16x4_f32 v[208:211], v68, v90, v[208:211]
	v_mfma_f32_16x16x4_f32 v[212:215], v69, v90, v[212:215]
	v_cndmask_b32_e32 v183, v82, v83, vcc
	v_cndmask_b32_e64 v183, v183, v84, s[4:5]
	v_cndmask_b32_e64 v183, v183, v85, s[6:7]
	v_mul_f32_e32 v179, v235, v183
	v_fmac_f32_e32 v179, v228, v108
	v_fmac_f32_e32 v179, v229, v109
	v_fmac_f32_e32 v179, v230, v110
	v_fmac_f32_e32 v179, v231, v111
	ds_write_b32 v172, v179 offset:11264
	v_add_u32_e32 v170, 0x1080, v170
	v_add_u32_e32 v237, 0x1080, v237
	v_add_u32_e32 v95, 0x1080, v95
	s_waitcnt lgkmcnt(1)
	v_mfma_f32_16x16x4_f32 v[96:99], v22, v184, 0
	v_mfma_f32_16x16x4_f32 v[100:103], v23, v185, 0
	v_mfma_f32_16x16x4_f32 v[96:99], v24, v186, v[96:99]
	v_mfma_f32_16x16x4_f32 v[100:103], v25, v187, v[100:103]
	v_mul_f32_e32 v129, v132, v70
	v_mul_f32_e32 v130, v133, v71
	v_mul_f32_e32 v131, v134, v72
	v_mul_f32_e32 v153, v135, v73
	v_mfma_f32_16x16x4_f32 v[96:99], v26, v188, v[96:99]
	v_mfma_f32_16x16x4_f32 v[100:103], v27, v189, v[100:103]
	v_mfma_f32_16x16x4_f32 v[96:99], v28, v190, v[96:99]
	v_mfma_f32_16x16x4_f32 v[100:103], v29, v191, v[100:103]
	v_mul_f32_e64 v114, -v132, v136
	v_mul_f32_e64 v115, -v133, v137
	v_mul_f32_e64 v116, -v134, v138
	v_mul_f32_e64 v117, -v135, v139
	v_mfma_f32_16x16x4_f32 v[96:99], v30, v192, v[96:99]
	v_mfma_f32_16x16x4_f32 v[100:103], v31, v193, v[100:103]
	v_mfma_f32_16x16x4_f32 v[96:99], v32, v194, v[96:99]
	v_mfma_f32_16x16x4_f32 v[100:103], v33, v195, v[100:103]
	v_mul_f32_e32 v240, v238, v139
	v_rcp_f32_e32 v89, v240
	v_readfirstlane_b32 s0, v240
	ds_read_b32 v86, v87 offset:3072
	v_mfma_f32_16x16x4_f32 v[96:99], v34, v196, v[96:99]
	v_mfma_f32_16x16x4_f32 v[100:103], v35, v197, v[100:103]
	v_mfma_f32_16x16x4_f32 v[96:99], v36, v198, v[96:99]
	v_mfma_f32_16x16x4_f32 v[100:103], v37, v199, v[100:103]
	ds_read2_b32 v[62:63], v237 offset0:0 offset1:16
	ds_read2_b32 v[64:65], v237 offset0:32 offset1:48
	ds_read2_b32 v[66:67], v237 offset0:64 offset1:80
	ds_read2_b32 v[68:69], v237 offset0:96 offset1:112
	v_mfma_f32_16x16x4_f32 v[96:99], v38, v200, v[96:99]
	v_mfma_f32_16x16x4_f32 v[100:103], v39, v201, v[100:103]
	v_mfma_f32_16x16x4_f32 v[96:99], v40, v202, v[96:99]
	v_mfma_f32_16x16x4_f32 v[100:103], v41, v203, v[100:103]
	ds_read2st64_b32 v[74:75], v171 offset0:52 offset1:53
	ds_read2st64_b32 v[76:77], v171 offset0:54 offset1:55
	ds_read_b128 v[216:219], v175 offset:208
	ds_read_b128 v[220:223], v175 offset:464
	v_mfma_f32_16x16x4_f32 v[96:99], v42, v204, v[96:99]
	v_mfma_f32_16x16x4_f32 v[100:103], v43, v205, v[100:103]
	v_mfma_f32_16x16x4_f32 v[96:99], v44, v206, v[96:99]
	v_mfma_f32_16x16x4_f32 v[100:103], v45, v207, v[100:103]
	ds_read_b32 v235, v176 offset:464
	ds_read_b32 v236, v176 offset:720
	ds_read_b32 v234, v173 offset:3248
	ds_read_b64 v[232:233], v173 offset:3280
	v_mfma_f32_16x16x4_f32 v[96:99], v46, v208, v[96:99]
	v_mfma_f32_16x16x4_f32 v[100:103], v47, v209, v[100:103]
	v_mfma_f32_16x16x4_f32 v[96:99], v48, v210, v[96:99]
	v_mfma_f32_16x16x4_f32 v[100:103], v49, v211, v[100:103]
	ds_read_b128 v[224:227], v173 offset:3312
	ds_read_b128 v[228:231], v174 offset:3216
	v_mfma_f32_16x16x4_f32 v[96:99], v50, v212, v[96:99]
	v_mfma_f32_16x16x4_f32 v[100:103], v51, v213, v[100:103]
	v_mfma_f32_16x16x4_f32 v[96:99], v52, v214, v[96:99]
	v_mfma_f32_16x16x4_f32 v[100:103], v53, v215, v[100:103]
	s_nop 7
	s_nop 1
	v_pk_mul_f32 v[100:101], v[100:101], v[238:239] op_sel_hi:[1,0]
	v_pk_mul_f32 v[102:103], v[102:103], v[238:239] op_sel_hi:[1,0]
	v_pk_fma_f32 v[78:79], v[96:97], v[238:239], v[100:101] op_sel_hi:[1,0,1]
	v_pk_fma_f32 v[80:81], v[98:99], v[238:239], v[102:103] op_sel_hi:[1,0,1]
	v_pk_fma_f32 v[96:97], v[96:97], v[238:239], v[100:101] op_sel_hi:[1,0,1]
	v_pk_fma_f32 v[98:99], v[98:99], v[238:239], v[102:103] op_sel_hi:[1,0,1]
	s_nop 0
	v_permlane32_swap_b32_e32 v96, v78
	v_permlane32_swap_b32_e32 v97, v79
	v_permlane32_swap_b32_e32 v98, v80
	v_permlane32_swap_b32_e32 v99, v81
	v_mov_b32_e32 v82, v96
	v_mov_b32_e32 v83, v97
	v_mov_b32_e32 v84, v98
	v_mov_b32_e32 v85, v99
	s_nop 0
	v_permlane16_swap_b32_e32 v96, v82
	v_permlane16_swap_b32_e32 v97, v83
	v_permlane16_swap_b32_e32 v98, v84
	v_permlane16_swap_b32_e32 v99, v85
	v_fma_f32 v108, v114, v96, v129
	v_fma_f32 v109, v115, v97, v130
	v_fma_f32 v110, v116, v98, v131
	v_fma_f32 v111, v117, v99, v153
	v_fma_f32 v109, -v150, v108, v109
	v_fma_f32 v110, -v148, v108, v110
	v_fma_f32 v111, -v140, v108, v111
	v_fma_f32 v110, -v149, v109, v110
	v_fma_f32 v111, -v141, v109, v111
	v_fma_f32 v111, -v142, v110, v111
	v_cndmask_b32_e32 v182, v108, v109, vcc
	v_cndmask_b32_e64 v182, v182, v110, s[4:5]
	v_cndmask_b32_e64 v182, v182, v111, s[6:7]
	v_mul_f32_e32 v182, v152, v182
	s_cmp_lt_u32 s0, 0x2b800000
	s_cbranch_scc0 .Lgdn_nomat_6_0
	v_pk_mul_f32 v[184:185], v[184:185], v[240:241] op_sel_hi:[1,0]
	v_pk_mul_f32 v[186:187], v[186:187], v[240:241] op_sel_hi:[1,0]
	v_pk_mul_f32 v[188:189], v[188:189], v[240:241] op_sel_hi:[1,0]
	v_pk_mul_f32 v[190:191], v[190:191], v[240:241] op_sel_hi:[1,0]
	v_pk_mul_f32 v[192:193], v[192:193], v[240:241] op_sel_hi:[1,0]
	v_pk_mul_f32 v[194:195], v[194:195], v[240:241] op_sel_hi:[1,0]
	v_pk_mul_f32 v[196:197], v[196:197], v[240:241] op_sel_hi:[1,0]
	v_pk_mul_f32 v[198:199], v[198:199], v[240:241] op_sel_hi:[1,0]
	v_pk_mul_f32 v[200:201], v[200:201], v[240:241] op_sel_hi:[1,0]
	v_pk_mul_f32 v[202:203], v[202:203], v[240:241] op_sel_hi:[1,0]
	v_pk_mul_f32 v[204:205], v[204:205], v[240:241] op_sel_hi:[1,0]
	v_pk_mul_f32 v[206:207], v[206:207], v[240:241] op_sel_hi:[1,0]
	v_pk_mul_f32 v[208:209], v[208:209], v[240:241] op_sel_hi:[1,0]
	v_pk_mul_f32 v[210:211], v[210:211], v[240:241] op_sel_hi:[1,0]
	v_pk_mul_f32 v[212:213], v[212:213], v[240:241] op_sel_hi:[1,0]
	v_pk_mul_f32 v[214:215], v[214:215], v[240:241] op_sel_hi:[1,0]
	v_mov_b32_e32 v240, 1.0
	v_mov_b32_e32 v89, 1.0

.Lgdn_nomat_6_1:
	v_mov_b32_e32 v238, v240
	v_mul_f32_e32 v90, v182, v89
	s_nop 1
	v_mfma_f32_16x16x4_f32 v[184:187], v62, v90, v[184:187]
	v_mfma_f32_16x16x4_f32 v[188:191], v63, v90, v[188:191]
	v_mfma_f32_16x16x4_f32 v[192:195], v64, v90, v[192:195]
	v_mfma_f32_16x16x4_f32 v[196:199], v65, v90, v[196:199]
	v_mfma_f32_16x16x4_f32 v[200:203], v66, v90, v[200:203]
	v_mfma_f32_16x16x4_f32 v[204:207], v67, v90, v[204:207]
	v_mfma_f32_16x16x4_f32 v[208:211], v68, v90, v[208:211]
	v_mfma_f32_16x16x4_f32 v[212:215], v69, v90, v[212:215]
	v_cndmask_b32_e32 v183, v82, v83, vcc
	v_cndmask_b32_e64 v183, v183, v84, s[4:5]
	v_cndmask_b32_e64 v183, v183, v85, s[6:7]
	v_mul_f32_e32 v179, v235, v183
	v_fmac_f32_e32 v179, v228, v108
	v_fmac_f32_e32 v179, v229, v109
	v_fmac_f32_e32 v179, v230, v110
	v_fmac_f32_e32 v179, v231, v111
	ds_write_b32 v172, v179 offset:13312
	v_add_u32_e32 v170, 0x1080, v170
	v_add_u32_e32 v237, 0x1080, v237
	v_add_u32_e32 v95, 0x1080, v95
	s_waitcnt lgkmcnt(1)
	v_mfma_f32_16x16x4_f32 v[96:99], v22, v184, 0
	v_mfma_f32_16x16x4_f32 v[100:103], v23, v185, 0
	v_mfma_f32_16x16x4_f32 v[96:99], v24, v186, v[96:99]
	v_mfma_f32_16x16x4_f32 v[100:103], v25, v187, v[100:103]
	v_mul_f32_e32 v129, v132, v70
	v_mul_f32_e32 v130, v133, v71
	v_mul_f32_e32 v131, v134, v72
	v_mul_f32_e32 v153, v135, v73
	v_mfma_f32_16x16x4_f32 v[96:99], v26, v188, v[96:99]
	v_mfma_f32_16x16x4_f32 v[100:103], v27, v189, v[100:103]
	v_mfma_f32_16x16x4_f32 v[96:99], v28, v190, v[96:99]
	v_mfma_f32_16x16x4_f32 v[100:103], v29, v191, v[100:103]
	v_mul_f32_e64 v114, -v132, v136
	v_mul_f32_e64 v115, -v133, v137
	v_mul_f32_e64 v116, -v134, v138
	v_mul_f32_e64 v117, -v135, v139
	v_mfma_f32_16x16x4_f32 v[96:99], v30, v192, v[96:99]
	v_mfma_f32_16x16x4_f32 v[100:103], v31, v193, v[100:103]
	v_mfma_f32_16x16x4_f32 v[96:99], v32, v194, v[96:99]
	v_mfma_f32_16x16x4_f32 v[100:103], v33, v195, v[100:103]
	v_mul_f32_e32 v240, v238, v139
	v_rcp_f32_e32 v89, v240
	v_readfirstlane_b32 s0, v240
	ds_read_b32 v86, v87 offset:3584
	v_mfma_f32_16x16x4_f32 v[96:99], v34, v196, v[96:99]
	v_mfma_f32_16x16x4_f32 v[100:103], v35, v197, v[100:103]
	v_mfma_f32_16x16x4_f32 v[96:99], v36, v198, v[96:99]
	v_mfma_f32_16x16x4_f32 v[100:103], v37, v199, v[100:103]
	ds_read2_b32 v[62:63], v237 offset0:0 offset1:16
	ds_read2_b32 v[64:65], v237 offset0:32 offset1:48
	ds_read2_b32 v[66:67], v237 offset0:64 offset1:80
	ds_read2_b32 v[68:69], v237 offset0:96 offset1:112
	v_mfma_f32_16x16x4_f32 v[96:99], v38, v200, v[96:99]
	v_mfma_f32_16x16x4_f32 v[100:103], v39, v201, v[100:103]
	v_mfma_f32_16x16x4_f32 v[96:99], v40, v202, v[96:99]
	v_mfma_f32_16x16x4_f32 v[100:103], v41, v203, v[100:103]
	ds_read2st64_b32 v[74:75], v171 offset0:60 offset1:61
	ds_read2st64_b32 v[76:77], v171 offset0:62 offset1:63
	ds_read_b128 v[216:219], v175 offset:240
	ds_read_b128 v[220:223], v175 offset:496
	v_mfma_f32_16x16x4_f32 v[96:99], v42, v204, v[96:99]
	v_mfma_f32_16x16x4_f32 v[100:103], v43, v205, v[100:103]
	v_mfma_f32_16x16x4_f32 v[96:99], v44, v206, v[96:99]
	v_mfma_f32_16x16x4_f32 v[100:103], v45, v207, v[100:103]
	ds_read_b32 v235, v176 offset:496
	ds_read_b32 v236, v176 offset:752
	ds_read_b32 v234, v173 offset:3760
	ds_read_b64 v[232:233], v173 offset:3792
	v_mfma_f32_16x16x4_f32 v[96:99], v46, v208, v[96:99]
	v_mfma_f32_16x16x4_f32 v[100:103], v47, v209, v[100:103]
	v_mfma_f32_16x16x4_f32 v[96:99], v48, v210, v[96:99]
	v_mfma_f32_16x16x4_f32 v[100:103], v49, v211, v[100:103]
	ds_read_b128 v[224:227], v173 offset:3824
	ds_read_b128 v[228:231], v174 offset:3728
	v_mfma_f32_16x16x4_f32 v[96:99], v50, v212, v[96:99]
	v_mfma_f32_16x16x4_f32 v[100:103], v51, v213, v[100:103]
	v_mfma_f32_16x16x4_f32 v[96:99], v52, v214, v[96:99]
	v_mfma_f32_16x16x4_f32 v[100:103], v53, v215, v[100:103]
	s_nop 7
	s_nop 1
	v_pk_mul_f32 v[100:101], v[100:101], v[238:239] op_sel_hi:[1,0]
	v_pk_mul_f32 v[102:103], v[102:103], v[238:239] op_sel_hi:[1,0]
	v_pk_fma_f32 v[78:79], v[96:97], v[238:239], v[100:101] op_sel_hi:[1,0,1]
	v_pk_fma_f32 v[80:81], v[98:99], v[238:239], v[102:103] op_sel_hi:[1,0,1]
	v_pk_fma_f32 v[96:97], v[96:97], v[238:239], v[100:101] op_sel_hi:[1,0,1]
	v_pk_fma_f32 v[98:99], v[98:99], v[238:239], v[102:103] op_sel_hi:[1,0,1]
	s_nop 0
	v_permlane32_swap_b32_e32 v96, v78
	v_permlane32_swap_b32_e32 v97, v79
	v_permlane32_swap_b32_e32 v98, v80
	v_permlane32_swap_b32_e32 v99, v81
	v_mov_b32_e32 v82, v96
	v_mov_b32_e32 v83, v97
	v_mov_b32_e32 v84, v98
	v_mov_b32_e32 v85, v99
	s_nop 0
	v_permlane16_swap_b32_e32 v96, v82
	v_permlane16_swap_b32_e32 v97, v83
	v_permlane16_swap_b32_e32 v98, v84
	v_permlane16_swap_b32_e32 v99, v85
	v_fma_f32 v108, v114, v96, v129
	v_fma_f32 v109, v115, v97, v130
	v_fma_f32 v110, v116, v98, v131
	v_fma_f32 v111, v117, v99, v153
	v_fma_f32 v109, -v150, v108, v109
	v_fma_f32 v110, -v148, v108, v110
	v_fma_f32 v111, -v140, v108, v111
	v_fma_f32 v110, -v149, v109, v110
	v_fma_f32 v111, -v141, v109, v111
	v_fma_f32 v111, -v142, v110, v111
	v_cndmask_b32_e32 v182, v108, v109, vcc
	v_cndmask_b32_e64 v182, v182, v110, s[4:5]
	v_cndmask_b32_e64 v182, v182, v111, s[6:7]
	v_mul_f32_e32 v182, v152, v182
	s_cmp_lt_u32 s0, 0x2b800000
	s_cbranch_scc0 .Lgdn_nomat_7_0
	v_pk_mul_f32 v[184:185], v[184:185], v[240:241] op_sel_hi:[1,0]
	v_pk_mul_f32 v[186:187], v[186:187], v[240:241] op_sel_hi:[1,0]
	v_pk_mul_f32 v[188:189], v[188:189], v[240:241] op_sel_hi:[1,0]
	v_pk_mul_f32 v[190:191], v[190:191], v[240:241] op_sel_hi:[1,0]
	v_pk_mul_f32 v[192:193], v[192:193], v[240:241] op_sel_hi:[1,0]
	v_pk_mul_f32 v[194:195], v[194:195], v[240:241] op_sel_hi:[1,0]
	v_pk_mul_f32 v[196:197], v[196:197], v[240:241] op_sel_hi:[1,0]
	v_pk_mul_f32 v[198:199], v[198:199], v[240:241] op_sel_hi:[1,0]
	v_pk_mul_f32 v[200:201], v[200:201], v[240:241] op_sel_hi:[1,0]
	v_pk_mul_f32 v[202:203], v[202:203], v[240:241] op_sel_hi:[1,0]
	v_pk_mul_f32 v[204:205], v[204:205], v[240:241] op_sel_hi:[1,0]
	v_pk_mul_f32 v[206:207], v[206:207], v[240:241] op_sel_hi:[1,0]
	v_pk_mul_f32 v[208:209], v[208:209], v[240:241] op_sel_hi:[1,0]
	v_pk_mul_f32 v[210:211], v[210:211], v[240:241] op_sel_hi:[1,0]
	v_pk_mul_f32 v[212:213], v[212:213], v[240:241] op_sel_hi:[1,0]
	v_pk_mul_f32 v[214:215], v[214:215], v[240:241] op_sel_hi:[1,0]
	v_mov_b32_e32 v240, 1.0
	v_mov_b32_e32 v89, 1.0
